# phases 0/1: nt hint on the once-read f32 weight loads (adaLN weights, Fourier-fold and transpose items), on top of the nt ninth-round conversion stream
# baseline (speedup 1.0000x reference)
.LBB0_15:
	v_add_co_u32_e32 v82, vcc, 0xfffa3000, v76
	s_add_i32 s6, s29, 0x1058
	s_nop 0
	v_addc_co_u32_e32 v83, vcc, -1, v77, vcc
	v_add_co_u32_e32 v118, vcc, 0xfffa6000, v76
	s_add_i32 s4, s29, 0x2058
	s_add_i32 s5, s29, 0x3058
	s_add_i32 s31, s29, 0x1068
	s_add_i32 s7, s29, 0x2068
	s_add_i32 s30, s29, 0x3068
	s_add_i32 s35, s29, 0x103c
	s_add_i32 s36, s29, 0x1044
	s_add_i32 s37, s29, 0x202c
	s_add_i32 s38, s29, 0x302c
	s_add_i32 s40, s29, 0x3034
	s_add_i32 s41, s29, 0x203c
	s_add_i32 s42, s29, 0x303c
	s_add_i32 s43, s29, 0x2044
	s_add_i32 s44, s29, 0x3044
	s_add_i32 s47, s29, 0x104c
	v_addc_co_u32_e32 v119, vcc, -1, v77, vcc
	v_mov_b32_e32 v2, s29
	s_add_i32 s33, s29, 0x102c
	s_add_i32 s34, s29, 0x1034
	s_add_i32 s39, s29, 0x2034
	s_add_i32 s45, s29, 0x204c
	s_add_i32 s46, s29, 0x304c
	v_mov_b32_e32 v6, s6
	v_mov_b32_e32 v7, s31
	v_mov_b32_e32 v10, s4
	v_mov_b32_e32 v11, s5
	v_mov_b32_e32 v12, s7
	v_mov_b32_e32 v13, s30
	v_mov_b32_e32 v94, s35
	v_mov_b32_e32 v95, s36
	v_mov_b32_e32 v100, s37
	v_mov_b32_e32 v101, s38
	v_mov_b32_e32 v98, s40
	v_mov_b32_e32 v99, s41
	v_mov_b32_e32 v104, s42
	v_mov_b32_e32 v112, s43
	v_mov_b32_e32 v113, s44
	v_mov_b32_e32 v173, s47
	v_add_co_u32_e32 v172, vcc, 0xfffa9000, v76
	global_load_dword v84, v[76:77], off nt
	ds_read_b128 v[114:117], v2
	ds_read_b128 v[122:125], v2 offset:16
	ds_read_b128 v[46:49], v2 offset:4096
	ds_read_b128 v[18:21], v2 offset:4112
	ds_read_b128 v[126:129], v2 offset:8192
	ds_read_b128 v[130:133], v2 offset:8208
	ds_read_b128 v[54:57], v2 offset:12288
	ds_read_b128 v[26:29], v2 offset:12304
	ds_read_b128 v[62:65], v2 offset:16384
	ds_read_b128 v[34:37], v2 offset:16400
	ds_read_b96 v[150:152], v2 offset:32
	ds_read2_b32 v[158:159], v2 offset0:11 offset1:12
	ds_read2_b64 v[134:137], v2 offset0:13 offset1:14
	ds_read_b64 v[160:161], v2 offset:120
	ds_read_b96 v[66:68], v2 offset:4128
	ds_read_b32 v91, v2 offset:4180
	ds_read_b64 v[86:87], v2 offset:4216
	ds_read_b32 v92, v2 offset:8276
	ds_read_b64 v[162:163], v2 offset:8312
	ds_read_b96 v[154:156], v2 offset:8224
	ds_read_b32 v93, v2 offset:12372
	ds_read_b64 v[88:89], v2 offset:12408
	ds_read_b96 v[70:72], v2 offset:12320
	ds_read_b128 v[58:61], v2 offset:16416
	ds_read_b128 v[30:33], v2 offset:16432
	v_mov_b32_e32 v69, s33
	v_mov_b32_e32 v73, s34
	v_mov_b32_e32 v121, s39
	ds_read2_b32 v[164:165], v2 offset0:13 offset1:14
	ds_read2_b32 v[166:167], v2 offset0:15 offset1:16
	ds_read2_b32 v[168:169], v2 offset0:17 offset1:18
	ds_read2_b32 v[170:171], v2 offset0:19 offset1:20
	v_mov_b32_e32 v153, s45
	v_mov_b32_e32 v157, s46
	ds_read_b128 v[50:53], v2 offset:16448
	ds_read_b128 v[22:25], v2 offset:16464
	ds_read2_b64 v[138:141], v2 offset0:11 offset1:12
	ds_read_b32 v90, v2 offset:84
	ds_read_b128 v[14:17], v2 offset:16480
	ds_read_b128 v[2:5], v2 offset:16496
	ds_read2_b64 v[38:41], v6 offset1:1
	ds_read2_b64 v[6:9], v7 offset1:1
	ds_read2_b64 v[142:145], v10 offset1:1
	ds_read2_b64 v[42:45], v11 offset1:1
	ds_read2_b64 v[146:149], v12 offset1:1
	ds_read2_b64 v[10:13], v13 offset1:1
	ds_read2_b32 v[110:111], v69 offset1:1
	ds_read2_b32 v[106:107], v73 offset1:1
	ds_read2_b32 v[102:103], v94 offset1:1
	ds_read2_b32 v[96:97], v95 offset1:1
	ds_read2_b32 v[108:109], v98 offset1:1
	ds_read2_b32 v[174:175], v99 offset1:1
	ds_read2_b32 v[104:105], v104 offset1:1
	ds_read2_b32 v[176:177], v112 offset1:1
	ds_read2_b32 v[98:99], v113 offset1:1
	ds_read2_b32 v[178:179], v153 offset1:1
	ds_read2_b32 v[94:95], v157 offset1:1
	ds_read2_b32 v[180:181], v100 offset1:1
	ds_read2_b32 v[112:113], v101 offset1:1
	ds_read2_b32 v[182:183], v121 offset1:1
	ds_read2_b32 v[100:101], v173 offset1:1
	v_addc_co_u32_e32 v173, vcc, -1, v77, vcc
	global_load_dword v184, v[82:83], off nt
	global_load_dword v186, v[118:119], off nt
	v_add_co_u32_e32 v82, vcc, 0xfffac000, v76
	s_waitcnt lgkmcnt(14)
	v_mov_b32_e32 v198, v126
	v_addc_co_u32_e32 v83, vcc, -1, v77, vcc
	v_add_co_u32_e32 v188, vcc, 0xfffaf000, v76
	v_mov_b32_e32 v126, v128
	s_nop 0
	v_addc_co_u32_e32 v189, vcc, -1, v77, vcc
	v_add_co_u32_e32 v192, vcc, 0xfffb2000, v76
	v_mov_b32_e32 v199, v54
	s_nop 0
	v_addc_co_u32_e32 v193, vcc, -1, v77, vcc
	v_add_co_u32_e32 v128, vcc, 0xfffb5000, v76
	v_mov_b32_e32 v54, v127
	v_mov_b32_e32 v127, v56
	v_mov_b32_e32 v56, v129
	v_addc_co_u32_e32 v129, vcc, -1, v77, vcc
	v_mov_b32_e32 v153, v70
	v_mov_b32_e32 v70, v155
	v_mov_b32_e32 v155, v72
	v_mov_b32_e32 v72, v162
	v_add_co_u32_e32 v162, vcc, 0xfffb8000, v76
	v_mov_b32_e32 v73, v88
	v_mov_b32_e32 v88, v163
	v_addc_co_u32_e32 v163, vcc, -1, v77, vcc
	v_mov_b32_e32 v200, v122
	v_mov_b32_e32 v122, v124
	v_mov_b32_e32 v124, v130
	v_mov_b32_e32 v130, v132
	v_mov_b32_e32 v132, v150
	v_mov_b32_e32 v150, v152
	v_mov_b32_e32 v152, v154
	v_mov_b32_e32 v154, v156
	v_mov_b32_e32 v156, v170
	v_add_co_u32_e32 v170, vcc, 0xfffbb000, v76
	s_waitcnt lgkmcnt(0)
	v_mov_b32_e32 v157, v100
	v_mov_b32_e32 v100, v171
	v_addc_co_u32_e32 v171, vcc, -1, v77, vcc
	global_load_dword v172, v[172:173], off nt
	s_nop 0
	global_load_dword v190, v[82:83], off nt
	v_mov_b32_e32 v194, v114
	v_mov_b32_e32 v201, v18
	v_mov_b32_e32 v18, v123
	v_mov_b32_e32 v123, v20
	v_mov_b32_e32 v20, v125
	v_mov_b32_e32 v125, v26
	v_mov_b32_e32 v26, v131
	v_mov_b32_e32 v131, v28
	v_mov_b32_e32 v28, v133
	v_mov_b32_e32 v133, v66
	v_mov_b32_e32 v114, v134
	v_mov_b32_e32 v66, v151
	v_mov_b32_e32 v151, v68
	v_mov_b32_e32 v134, v158
	v_mov_b32_e32 v68, v160
	global_load_dword v158, v[188:189], off nt
	global_load_dword v160, v[192:193], off nt
	v_mov_b32_e32 v188, v142
	v_mov_b32_e32 v142, v144
	v_mov_b32_e32 v144, v146
	v_mov_b32_e32 v146, v148
	v_mov_b32_e32 v148, v180
	v_mov_b32_e32 v180, v174
	v_add_co_u32_e32 v174, vcc, 0xfffbe000, v76
	v_mov_b32_e32 v189, v42
	v_mov_b32_e32 v42, v143
	v_mov_b32_e32 v143, v44
	v_mov_b32_e32 v44, v145
	v_mov_b32_e32 v145, v10
	v_mov_b32_e32 v10, v147
	v_mov_b32_e32 v147, v12
	v_mov_b32_e32 v12, v149
	v_mov_b32_e32 v149, v112
	v_mov_b32_e32 v112, v181
	v_mov_b32_e32 v181, v104
	v_mov_b32_e32 v104, v175
	v_addc_co_u32_e32 v175, vcc, -1, v77, vcc
	v_mov_b32_e32 v118, v138
	v_mov_b32_e32 v138, v166
	v_mov_b32_e32 v166, v176
	v_add_co_u32_e32 v176, vcc, 0xfffc1000, v76
	v_mov_b32_e32 v119, v38
	v_mov_b32_e32 v38, v139
	v_mov_b32_e32 v139, v102
	v_mov_b32_e32 v102, v167
	v_mov_b32_e32 v167, v98
	v_mov_b32_e32 v98, v177
	v_addc_co_u32_e32 v177, vcc, -1, v77, vcc
	v_mov_b32_e32 v196, v116
	v_mov_b32_e32 v116, v140
	v_mov_b32_e32 v140, v168
	v_mov_b32_e32 v168, v178
	v_add_co_u32_e32 v178, vcc, 0xfffc4000, v76
	v_mov_b32_e32 v197, v48
	v_mov_b32_e32 v48, v117
	v_mov_b32_e32 v117, v40
	v_mov_b32_e32 v40, v141
	v_mov_b32_e32 v141, v96
	v_mov_b32_e32 v96, v169
	v_mov_b32_e32 v169, v94
	v_mov_b32_e32 v94, v179
	v_addc_co_u32_e32 v179, vcc, -1, v77, vcc
	v_mov_b32_e32 v82, v136
	v_mov_b32_e32 v136, v164
	v_mov_b32_e32 v164, v182
	v_add_co_u32_e32 v182, vcc, 0xfffc7000, v76
	v_mov_b32_e32 v83, v8
	v_mov_b32_e32 v8, v137
	v_mov_b32_e32 v137, v106
	v_mov_b32_e32 v106, v165
	v_mov_b32_e32 v165, v108
	v_mov_b32_e32 v108, v183
	v_addc_co_u32_e32 v183, vcc, -1, v77, vcc
	v_add_co_u32_e32 v192, vcc, 0xfffca000, v76
	global_load_dword v128, v[128:129], off nt
	s_nop 0
	global_load_dword v162, v[162:163], off nt
	v_addc_co_u32_e32 v193, vcc, -1, v77, vcc
	v_add_co_u32_e32 v202, vcc, 0xfffcd000, v76
	global_load_dword v170, v[170:171], off nt
	s_nop 0
	global_load_dword v174, v[174:175], off nt
	v_addc_co_u32_e32 v203, vcc, -1, v77, vcc
	v_add_co_u32_e32 v204, vcc, 0xfffd0000, v76
	global_load_dword v176, v[176:177], off nt
	s_nop 0
	global_load_dword v178, v[178:179], off nt
	v_addc_co_u32_e32 v205, vcc, -1, v77, vcc
	v_add_co_u32_e32 v206, vcc, 0xfffd3000, v76
	s_mov_b64 s[4:5], vcc
	v_add_co_u32_e32 v208, vcc, 0xfffd6000, v76
	s_mov_b64 s[6:7], vcc
	v_addc_co_u32_e64 v207, vcc, -1, v77, s[4:5]
	v_add_co_u32_e32 v210, vcc, 0xfffd9000, v76
	s_mov_b64 s[4:5], vcc
	v_addc_co_u32_e64 v209, vcc, -1, v77, s[6:7]
	v_add_co_u32_e32 v212, vcc, 0xfffdc000, v76
	s_mov_b64 s[6:7], vcc
	v_addc_co_u32_e64 v211, vcc, -1, v77, s[4:5]
	v_add_co_u32_e32 v214, vcc, 0xfffdf000, v76
	s_mov_b64 s[4:5], vcc
	v_addc_co_u32_e64 v213, vcc, -1, v77, s[6:7]
	v_add_co_u32_e32 v218, vcc, 0xfffe2000, v76
	s_mov_b64 s[6:7], vcc
	v_addc_co_u32_e64 v215, vcc, -1, v77, s[4:5]
	v_add_co_u32_e32 v220, vcc, 0xfffe5000, v76
	global_load_dword v182, v[182:183], off nt
	s_nop 0
	global_load_dword v192, v[192:193], off nt
	v_addc_co_u32_e32 v221, vcc, -1, v77, vcc
	v_add_co_u32_e32 v222, vcc, 0xfffe8000, v76
	global_load_dword v202, v[202:203], off nt
	s_nop 0
	global_load_dword v204, v[204:205], off nt
	v_addc_co_u32_e32 v223, vcc, -1, v77, vcc
	global_load_dword v206, v[206:207], off nt
	v_add_co_u32_e32 v224, vcc, 0xfffeb000, v76
	global_load_dword v208, v[208:209], off nt
	s_nop 0
	v_addc_co_u32_e32 v225, vcc, -1, v77, vcc
	global_load_dword v210, v[210:211], off nt
	v_addc_co_u32_e64 v219, s[4:5], -1, v77, s[6:7]
	global_load_dword v212, v[212:213], off nt
	v_mov_b32_e32 v195, v46
	global_load_dword v214, v[214:215], off nt
	s_nop 0
	global_load_dword v220, v[220:221], off nt
	s_nop 0
	global_load_dword v221, v[222:223], off nt
	s_nop 0
	global_load_dword v218, v[218:219], off nt
	v_add_co_u32_e32 v222, vcc, 0xfffee000, v76
	v_mov_b32_e32 v46, v115
	s_nop 0
	v_addc_co_u32_e32 v223, vcc, -1, v77, vcc
	v_add_co_u32_e32 v226, vcc, 0xffff1000, v76
	global_load_dword v224, v[224:225], off nt
	s_nop 0
	global_load_dword v225, v[222:223], off nt
	v_addc_co_u32_e32 v227, vcc, -1, v77, vcc
	v_add_co_u32_e32 v222, vcc, 0xffff4000, v76
	s_waitcnt vmcnt(25)
	v_pk_fma_f32 v[78:79], v[184:185], v[194:195], v[78:79] op_sel_hi:[0,1,1]
	v_addc_co_u32_e32 v223, vcc, -1, v77, vcc
	v_add_co_u32_e32 v228, vcc, 0xffff7000, v76
	global_load_dword v226, v[226:227], off nt
	s_nop 0
	global_load_dword v227, v[222:223], off nt
	v_addc_co_u32_e32 v229, vcc, -1, v77, vcc
	v_add_co_u32_e32 v222, vcc, 0xffffa000, v76
	global_load_dword v228, v[228:229], off nt
	s_nop 0
	v_addc_co_u32_e32 v223, vcc, -1, v77, vcc
	v_add_co_u32_e32 v230, vcc, 0xffffd000, v76
	v_pk_fma_f32 v[80:81], v[184:185], v[198:199], v[80:81] op_sel_hi:[0,1,1]
	s_nop 0
	v_addc_co_u32_e32 v231, vcc, -1, v77, vcc
	global_load_dword v229, v[222:223], off nt
	s_nop 0
	global_load_dword v222, v[230:231], off nt
	s_waitcnt vmcnt(29)
	v_pk_fma_f32 v[46:47], v[186:187], v[46:47], v[78:79] op_sel_hi:[0,1,1]
	v_pk_fma_f32 v[54:55], v[186:187], v[54:55], v[80:81] op_sel_hi:[0,1,1]
	v_fmac_f32_e32 v120, v184, v62
	s_waitcnt vmcnt(28)
	v_pk_fma_f32 v[46:47], v[172:173], v[196:197], v[46:47] op_sel_hi:[0,1,1]
	v_pk_fma_f32 v[54:55], v[172:173], v[126:127], v[54:55] op_sel_hi:[0,1,1]
	v_fmac_f32_e32 v120, v186, v63
	s_waitcnt vmcnt(27)
	v_pk_fma_f32 v[46:47], v[190:191], v[48:49], v[46:47] op_sel_hi:[0,1,1]
	v_pk_fma_f32 v[48:49], v[190:191], v[56:57], v[54:55] op_sel_hi:[0,1,1]
	v_fmac_f32_e32 v120, v172, v64
	s_waitcnt vmcnt(26)
	v_pk_fma_f32 v[46:47], v[158:159], v[200:201], v[46:47] op_sel_hi:[0,1,1]
	v_pk_fma_f32 v[48:49], v[158:159], v[124:125], v[48:49] op_sel_hi:[0,1,1]
	v_fmac_f32_e32 v120, v190, v65
	s_waitcnt vmcnt(25)
	v_pk_fma_f32 v[18:19], v[160:161], v[18:19], v[46:47] op_sel_hi:[0,1,1]
	v_pk_fma_f32 v[26:27], v[160:161], v[26:27], v[48:49] op_sel_hi:[0,1,1]
	v_fmac_f32_e32 v120, v158, v34
	s_waitcnt vmcnt(24)
	v_pk_fma_f32 v[18:19], v[128:129], v[122:123], v[18:19] op_sel_hi:[0,1,1]
	v_pk_fma_f32 v[26:27], v[128:129], v[130:131], v[26:27] op_sel_hi:[0,1,1]
	v_fmac_f32_e32 v120, v160, v35
	s_waitcnt vmcnt(23)
	v_pk_fma_f32 v[18:19], v[162:163], v[20:21], v[18:19] op_sel_hi:[0,1,1]
	v_pk_fma_f32 v[20:21], v[162:163], v[28:29], v[26:27] op_sel_hi:[0,1,1]
	v_fmac_f32_e32 v120, v128, v36
	s_waitcnt vmcnt(22)
	v_pk_fma_f32 v[18:19], v[170:171], v[132:133], v[18:19] op_sel_hi:[0,1,1]
	v_pk_fma_f32 v[20:21], v[170:171], v[152:153], v[20:21] op_sel_hi:[0,1,1]
	v_fmac_f32_e32 v120, v162, v37
	s_waitcnt vmcnt(21)
	v_pk_fma_f32 v[18:19], v[174:175], v[66:67], v[18:19] op_sel_hi:[0,1,1]
	v_pk_fma_f32 v[20:21], v[174:175], v[70:71], v[20:21] op_sel_hi:[0,1,1]
	v_mov_b32_e32 v115, v6
	v_mov_b32_e32 v6, v135
	v_mov_b32_e32 v135, v110
	v_fmac_f32_e32 v120, v170, v58
	s_waitcnt vmcnt(20)
	v_pk_fma_f32 v[18:19], v[176:177], v[150:151], v[18:19] op_sel_hi:[0,1,1]
	v_pk_fma_f32 v[20:21], v[176:177], v[154:155], v[20:21] op_sel_hi:[0,1,1]
	v_mov_b32_e32 v110, v159
	v_fmac_f32_e32 v120, v174, v59
	s_waitcnt vmcnt(19)
	v_pk_fma_f32 v[18:19], v[178:179], v[134:135], v[18:19] op_sel_hi:[0,1,1]
	v_pk_fma_f32 v[20:21], v[178:179], v[148:149], v[20:21] op_sel_hi:[0,1,1]
	v_fmac_f32_e32 v120, v176, v60
	s_waitcnt vmcnt(18)
	v_pk_fma_f32 v[18:19], v[182:183], v[110:111], v[18:19] op_sel_hi:[0,1,1]
	v_pk_fma_f32 v[20:21], v[182:183], v[112:113], v[20:21] op_sel_hi:[0,1,1]
	v_fmac_f32_e32 v120, v178, v61
	s_waitcnt vmcnt(17)
	v_pk_fma_f32 v[18:19], v[192:193], v[136:137], v[18:19] op_sel_hi:[0,1,1]
	v_pk_fma_f32 v[20:21], v[192:193], v[164:165], v[20:21] op_sel_hi:[0,1,1]
	v_fmac_f32_e32 v120, v182, v30
	s_waitcnt vmcnt(16)
	v_pk_fma_f32 v[18:19], v[202:203], v[106:107], v[18:19] op_sel_hi:[0,1,1]
	v_pk_fma_f32 v[20:21], v[202:203], v[108:109], v[20:21] op_sel_hi:[0,1,1]
	v_fmac_f32_e32 v120, v192, v31
	s_waitcnt vmcnt(15)
	v_pk_fma_f32 v[18:19], v[204:205], v[138:139], v[18:19] op_sel_hi:[0,1,1]
	v_pk_fma_f32 v[20:21], v[204:205], v[180:181], v[20:21] op_sel_hi:[0,1,1]
	v_fmac_f32_e32 v120, v202, v32
	s_waitcnt vmcnt(14)
	v_pk_fma_f32 v[18:19], v[206:207], v[102:103], v[18:19] op_sel_hi:[0,1,1]
	v_pk_fma_f32 v[20:21], v[206:207], v[104:105], v[20:21] op_sel_hi:[0,1,1]
	v_fmac_f32_e32 v120, v204, v33
	s_waitcnt vmcnt(13)
	v_pk_fma_f32 v[18:19], v[208:209], v[140:141], v[18:19] op_sel_hi:[0,1,1]
	v_pk_fma_f32 v[20:21], v[208:209], v[166:167], v[20:21] op_sel_hi:[0,1,1]
	v_fmac_f32_e32 v120, v206, v50
	s_waitcnt vmcnt(12)
	v_pk_fma_f32 v[18:19], v[210:211], v[96:97], v[18:19] op_sel_hi:[0,1,1]
	v_pk_fma_f32 v[20:21], v[210:211], v[98:99], v[20:21] op_sel_hi:[0,1,1]
	v_fmac_f32_e32 v120, v208, v51
	s_waitcnt vmcnt(11)
	v_pk_fma_f32 v[18:19], v[212:213], v[156:157], v[18:19] op_sel_hi:[0,1,1]
	v_pk_fma_f32 v[20:21], v[212:213], v[168:169], v[20:21] op_sel_hi:[0,1,1]
	v_fmac_f32_e32 v120, v210, v52
	s_waitcnt vmcnt(10)
	v_pk_fma_f32 v[18:19], v[214:215], v[100:101], v[18:19] op_sel_hi:[0,1,1]
	v_pk_fma_f32 v[20:21], v[214:215], v[94:95], v[20:21] op_sel_hi:[0,1,1]
	s_waitcnt vmcnt(7)
	v_mov_b32_e32 v215, v218
	v_fmac_f32_e32 v120, v212, v53
	v_pk_fma_f32 v[18:19], v[218:219], v[90:91], v[18:19] op_sel_hi:[0,1,1]
	v_pk_fma_f32 v[20:21], v[218:219], v[92:93], v[20:21] op_sel_hi:[0,1,1]
	v_pk_mul_f32 v[22:23], v[214:215], v[22:23]
	v_mov_b32_e32 v26, v221
	v_pk_fma_f32 v[18:19], v[220:221], v[118:119], v[18:19] op_sel_hi:[0,1,1]
	v_pk_fma_f32 v[20:21], v[220:221], v[188:189], v[20:21] op_sel_hi:[0,1,1]
	v_add_f32_e32 v27, v120, v22
	v_pk_mul_f32 v[24:25], v[220:221], v[24:25]
	v_pk_fma_f32 v[18:19], v[26:27], v[38:39], v[18:19] op_sel_hi:[0,1,1]
	v_pk_fma_f32 v[20:21], v[26:27], v[42:43], v[20:21] op_sel_hi:[0,1,1]
	v_add_f32_e32 v23, v27, v23
	s_waitcnt vmcnt(5)
	v_mov_b32_e32 v22, v225
	v_pk_fma_f32 v[18:19], v[224:225], v[116:117], v[18:19] op_sel_hi:[0,1,1]
	v_pk_fma_f32 v[20:21], v[224:225], v[142:143], v[20:21] op_sel_hi:[0,1,1]
	v_add_f32_e32 v23, v23, v24
	v_pk_mul_f32 v[14:15], v[224:225], v[14:15]
	v_pk_fma_f32 v[18:19], v[22:23], v[40:41], v[18:19] op_sel_hi:[0,1,1]
	v_pk_fma_f32 v[20:21], v[22:23], v[44:45], v[20:21] op_sel_hi:[0,1,1]
	v_add_f32_e32 v23, v23, v25
	s_waitcnt vmcnt(3)
	v_mov_b32_e32 v22, v227
	v_pk_fma_f32 v[18:19], v[226:227], v[114:115], v[18:19] op_sel_hi:[0,1,1]
	v_pk_fma_f32 v[20:21], v[226:227], v[144:145], v[20:21] op_sel_hi:[0,1,1]
	v_add_f32_e32 v23, v23, v14
	v_pk_mul_f32 v[16:17], v[226:227], v[16:17]
	v_pk_fma_f32 v[6:7], v[22:23], v[6:7], v[18:19] op_sel_hi:[0,1,1]
	v_pk_fma_f32 v[10:11], v[22:23], v[10:11], v[20:21] op_sel_hi:[0,1,1]
	v_add_f32_e32 v15, v23, v15
	s_waitcnt vmcnt(1)
	v_mov_b32_e32 v14, v229
	v_pk_fma_f32 v[6:7], v[228:229], v[82:83], v[6:7] op_sel_hi:[0,1,1]
	v_pk_fma_f32 v[10:11], v[228:229], v[146:147], v[10:11] op_sel_hi:[0,1,1]
	v_add_f32_e32 v15, v15, v16
	v_mov_b32_e32 v69, v86
	v_pk_mul_f32 v[2:3], v[228:229], v[2:3]
	v_pk_fma_f32 v[6:7], v[14:15], v[8:9], v[6:7] op_sel_hi:[0,1,1]
	v_pk_fma_f32 v[8:9], v[14:15], v[12:13], v[10:11] op_sel_hi:[0,1,1]
	v_add_f32_e32 v10, v15, v17
	s_waitcnt vmcnt(0)
	v_pk_fma_f32 v[6:7], v[222:223], v[68:69], v[6:7] op_sel_hi:[0,1,1]
	v_pk_fma_f32 v[8:9], v[222:223], v[72:73], v[8:9] op_sel_hi:[0,1,1]
	v_mov_b32_e32 v223, v84
	v_add_f32_e32 v2, v10, v2
	v_pk_mul_f32 v[4:5], v[222:223], v[4:5]
	v_add_f32_e32 v2, v2, v3
	s_add_i32 s28, s28, 32
	s_addk_i32 s29, 0x80
	v_mov_b32_e32 v86, v161
	v_add_f32_e32 v2, v2, v4
	s_cmpk_gt_u32 s28, 0x5f
	v_lshl_add_u64 v[76:77], v[76:77], 0, s[16:17]
	v_pk_fma_f32 v[78:79], v[84:85], v[86:87], v[6:7] op_sel_hi:[0,1,1]
	v_pk_fma_f32 v[80:81], v[84:85], v[88:89], v[8:9] op_sel_hi:[0,1,1]
	v_add_f32_e32 v120, v2, v5
	s_cbranch_scc0 .LBB0_15
	v_add_u32_e32 v2, s20, v85
	s_and_b64 vcc, exec, s[12:13]
	ds_write2st64_b32 v2, v78, v79 offset0:80 offset1:81
	ds_write2st64_b32 v2, v80, v81 offset0:82 offset1:83
	ds_write_b32 v2, v120 offset:21504
	s_waitcnt lgkmcnt(0)
	s_barrier
	s_cbranch_vccz .LBB0_13
	s_mul_i32 s4, s27, 0xc00
	v_add_u32_e32 v2, s4, v74
	v_ashrrev_i32_e32 v3, 31, v2
	v_lshl_add_u64 v[2:3], v[2:3], 2, s[10:11]
	global_load_dword v10, v[2:3], off nt
	v_add_u32_e32 v8, s21, v85
	ds_read2st64_b32 v[2:3], v8 offset0:80 offset1:85
	ds_read2st64_b32 v[4:5], v8 offset0:90 offset1:95
	ds_read2st64_b32 v[6:7], v8 offset0:100 offset1:105
	ds_read2st64_b32 v[8:9], v8 offset0:110 offset1:115
	s_mul_i32 s5, s27, 5
	s_waitcnt lgkmcnt(3)
	v_add_f32_e32 v2, 0, v2
	v_add_f32_e32 v2, v2, v3
	s_mul_hi_i32 s4, s27, 5
	s_add_u32 s5, s5, s18
	s_waitcnt lgkmcnt(2)
	v_add_f32_e32 v2, v2, v4
	s_addc_u32 s4, s4, s23
	v_add_f32_e32 v2, v2, v5
	s_mul_hi_u32 s6, s5, 0x3000
	s_mulk_i32 s4, 0x3000
	s_waitcnt lgkmcnt(1)
	v_add_f32_e32 v2, v2, v6
	s_mulk_i32 s5, 0x3000
	s_add_i32 s6, s6, s4
	v_add_f32_e32 v2, v2, v7
	s_add_u32 s4, s0, s5
	s_waitcnt lgkmcnt(0)
	v_add_f32_e32 v2, v2, v8
	s_addc_u32 s5, s1, s6
	v_add_f32_e32 v2, v2, v9
	s_waitcnt vmcnt(0)
	v_add_f32_e32 v4, v2, v10
	v_lshl_add_u64 v[2:3], v[74:75], 2, s[4:5]
	global_store_dword v[2:3], v4, off
	s_branch .LBB0_13

.LBB0_93:
	s_or_b32 s6, s4, s12
	s_mul_i32 s0, s6, 0x1f00
	s_or_b32 s4, s0, s13
	v_lshl_add_u64 v[12:13], s[4:5], 2, v[6:7]
	s_add_i32 s4, s69, s0
	v_lshl_add_u64 v[14:15], s[4:5], 2, v[6:7]
	s_add_i32 s4, s17, s0
	v_lshl_add_u64 v[16:17], s[4:5], 2, v[6:7]
	s_add_i32 s4, s18, s0
	v_lshl_add_u64 v[18:19], s[4:5], 2, v[6:7]
	s_add_i32 s4, s19, s0
	v_lshl_add_u64 v[20:21], s[4:5], 2, v[6:7]
	s_add_i32 s4, s20, s0
	v_lshl_add_u64 v[46:47], s[4:5], 2, v[6:7]
	s_add_i32 s4, s21, s0
	v_add_co_u32_e32 v12, vcc, 0x3000, v12
	v_lshl_add_u64 v[48:49], s[4:5], 2, v[6:7]
	s_add_i32 s4, s22, s0
	v_addc_co_u32_e32 v13, vcc, 0, v13, vcc
	v_lshl_add_u64 v[50:51], s[4:5], 2, v[6:7]
	s_add_i32 s4, s23, s0
	global_load_dword v45, v[12:13], off offset:1024 nt
	global_load_dword v52, v[14:15], off nt
	global_load_dword v53, v[16:17], off nt
	global_load_dword v54, v[18:19], off nt
	global_load_dword v55, v[20:21], off nt
	global_load_dword v56, v[46:47], off nt
	global_load_dword v57, v[48:49], off nt
	global_load_dword v58, v[50:51], off nt
	v_lshl_add_u64 v[12:13], s[4:5], 2, v[6:7]
	s_add_i32 s4, s34, s0
	v_lshl_add_u64 v[14:15], s[4:5], 2, v[6:7]
	s_add_i32 s4, s35, s0
	v_lshl_add_u64 v[16:17], s[4:5], 2, v[6:7]
	s_add_i32 s4, s43, s0
	v_lshl_add_u64 v[18:19], s[4:5], 2, v[6:7]
	s_add_i32 s4, s44, s0
	v_lshl_add_u64 v[20:21], s[4:5], 2, v[6:7]
	s_add_i32 s4, s45, s0
	v_lshl_add_u64 v[46:47], s[4:5], 2, v[6:7]
	s_add_i32 s4, s70, s0
	v_lshl_add_u64 v[48:49], s[4:5], 2, v[6:7]
	s_add_i32 s4, s46, s0
	v_lshl_add_u64 v[50:51], s[4:5], 2, v[6:7]
	s_add_i32 s4, s71, s0
	global_load_dword v59, v[12:13], off nt
	global_load_dword v60, v[14:15], off nt
	global_load_dword v61, v[16:17], off nt
	global_load_dword v62, v[18:19], off nt
	global_load_dword v63, v[20:21], off nt
	global_load_dword v64, v[46:47], off nt
	global_load_dword v65, v[48:49], off nt
	global_load_dword v66, v[50:51], off nt
	v_lshl_add_u64 v[12:13], s[4:5], 2, v[6:7]
	s_add_i32 s4, s47, s0
	v_lshl_add_u64 v[14:15], s[4:5], 2, v[6:7]
	s_add_i32 s4, s56, s0
	v_lshl_add_u64 v[16:17], s[4:5], 2, v[6:7]
	s_add_i32 s4, s57, s0
	v_lshl_add_u64 v[18:19], s[4:5], 2, v[6:7]
	s_add_i32 s4, s58, s0
	v_lshl_add_u64 v[20:21], s[4:5], 2, v[6:7]
	s_add_i32 s4, s59, s0
	v_lshl_add_u64 v[46:47], s[4:5], 2, v[6:7]
	s_add_i32 s4, s60, s0
	v_lshl_add_u64 v[48:49], s[4:5], 2, v[6:7]
	s_add_i32 s4, s61, s0
	v_lshl_add_u64 v[50:51], s[4:5], 2, v[6:7]
	s_add_i32 s4, s62, s0
	global_load_dword v67, v[12:13], off nt
	global_load_dword v69, v[14:15], off nt
	global_load_dword v70, v[16:17], off nt
	global_load_dword v71, v[18:19], off nt
	global_load_dword v72, v[20:21], off nt
	global_load_dword v73, v[46:47], off nt
	global_load_dword v74, v[48:49], off nt
	global_load_dword v75, v[50:51], off nt
	v_lshl_add_u64 v[12:13], s[4:5], 2, v[6:7]
	s_add_i32 s4, s63, s0
	v_lshl_add_u64 v[14:15], s[4:5], 2, v[6:7]
	s_add_i32 s4, s64, s0
	v_lshl_add_u64 v[16:17], s[4:5], 2, v[6:7]
	s_add_i32 s4, s65, s0
	v_lshl_add_u64 v[18:19], s[4:5], 2, v[6:7]
	s_add_i32 s4, s66, s0
	v_lshl_add_u64 v[20:21], s[4:5], 2, v[6:7]
	s_add_i32 s4, s67, s0
	v_lshl_add_u64 v[46:47], s[4:5], 2, v[6:7]
	s_add_i32 s4, s72, s0
	v_lshl_add_u64 v[48:49], s[4:5], 2, v[6:7]
	s_add_i32 s4, s68, s0
	v_lshl_add_u64 v[50:51], s[4:5], 2, v[6:7]
	global_load_dword v12, v[12:13], off nt
	s_nop 0
	global_load_dword v13, v[14:15], off nt
	s_nop 0
	global_load_dword v14, v[16:17], off nt
	global_load_dword v15, v[18:19], off nt
	s_nop 0
	global_load_dword v16, v[20:21], off nt
	global_load_dword v17, v[46:47], off nt
	global_load_dword v18, v[48:49], off nt
	global_load_dword v19, v[50:51], off nt
	s_xor_b64 s[0:1], s[8:9], -1
	s_mov_b32 s4, 0
	s_waitcnt vmcnt(30)
	ds_write2_b32 v3, v45, v52 offset1:65
	s_waitcnt vmcnt(28)
	ds_write2_b32 v3, v53, v54 offset0:130 offset1:195
	s_waitcnt vmcnt(26)
	ds_write2_b32 v30, v55, v56 offset0:4 offset1:69
	s_waitcnt vmcnt(24)
	ds_write2_b32 v30, v57, v58 offset0:134 offset1:199
	s_waitcnt vmcnt(22)
	ds_write2_b32 v31, v59, v60 offset0:8 offset1:73
	s_waitcnt vmcnt(20)
	ds_write2_b32 v31, v61, v62 offset0:138 offset1:203
	s_waitcnt vmcnt(18)
	ds_write2_b32 v32, v63, v64 offset0:12 offset1:77
	s_waitcnt vmcnt(16)
	ds_write2_b32 v32, v65, v66 offset0:142 offset1:207
	s_waitcnt vmcnt(14)
	ds_write2_b32 v33, v67, v69 offset0:16 offset1:81
	s_waitcnt vmcnt(12)
	ds_write2_b32 v33, v70, v71 offset0:146 offset1:211
	s_waitcnt vmcnt(10)
	ds_write2_b32 v34, v72, v73 offset0:20 offset1:85
	s_waitcnt vmcnt(8)
	ds_write2_b32 v34, v74, v75 offset0:150 offset1:215
	s_waitcnt vmcnt(6)
	ds_write2_b32 v35, v12, v13 offset0:24 offset1:89
	s_waitcnt vmcnt(4)
	ds_write2_b32 v35, v14, v15 offset0:154 offset1:219
	s_waitcnt vmcnt(2)
	ds_write2_b32 v36, v16, v17 offset0:28 offset1:93
	s_waitcnt vmcnt(0)
	ds_write2_b32 v36, v18, v19 offset0:158 offset1:223
	s_waitcnt lgkmcnt(0)
	v_mov_b32_e32 v14, 0
	v_mov_b32_e32 v12, 0
	v_mov_b32_e32 v15, v14
	v_mov_b32_e32 v16, v14
	v_mov_b32_e32 v17, v14
	v_mov_b32_e32 v20, v14
	v_mov_b32_e32 v21, v14
	v_mov_b32_e32 v18, v14
	v_mov_b32_e32 v19, v14

.LBB0_149:
	v_mov_b32_e32 v31, 0
	s_and_b64 vcc, exec, s[8:9]
	v_mov_b32_e32 v30, 0
	v_mov_b32_e32 v29, 0
	v_mov_b32_e32 v28, 0
	v_mov_b32_e32 v35, 0
	v_mov_b32_e32 v34, 0
	v_mov_b32_e32 v33, 0
	v_mov_b32_e32 v32, 0
	v_mov_b32_e32 v27, 0
	v_mov_b32_e32 v26, 0
	v_mov_b32_e32 v25, 0
	v_mov_b32_e32 v24, 0
	v_mov_b32_e32 v23, 0
	v_mov_b32_e32 v22, 0
	v_mov_b32_e32 v21, 0
	v_mov_b32_e32 v20, 0
	v_mov_b32_e32 v19, 0
	v_mov_b32_e32 v18, 0
	v_mov_b32_e32 v17, 0
	v_mov_b32_e32 v16, 0
	v_mov_b32_e32 v15, 0
	v_mov_b32_e32 v14, 0
	v_mov_b32_e32 v13, 0
	v_mov_b32_e32 v12, 0
	v_mov_b32_e32 v11, 0
	v_mov_b32_e32 v10, 0
	v_mov_b32_e32 v9, 0
	v_mov_b32_e32 v8, 0
	v_mov_b32_e32 v7, 0
	v_mov_b32_e32 v6, 0
	v_mov_b32_e32 v5, 0
	v_mov_b32_e32 v4, 0
	s_cbranch_vccz .LBB0_151
	v_lshlrev_b32_e32 v5, 1, v2
	v_lshlrev_b32_e32 v4, 4, v2
	v_and_b32_e32 v5, 12, v5
	v_and_b32_e32 v3, 28, v68
	v_and_or_b32 v4, v4, 16, v5
	v_cndmask_b32_e64 v3, v4, v3, s[4:5]
	v_add_u32_e32 v4, s13, v3
	v_lshrrev_b32_e32 v3, 3, v2
	v_mov_b32_e32 v5, 0
	v_add_u32_e32 v3, s16, v3
	v_mad_u64_u32 v[6:7], s[4:5], s6, v3, 0
	v_lshlrev_b64 v[28:29], 2, v[4:5]
	v_add_u32_e32 v4, 8, v3
	v_lshl_add_u64 v[6:7], v[6:7], 2, s[0:1]
	v_mad_u64_u32 v[4:5], s[4:5], s6, v4, 0
	v_lshl_add_u64 v[12:13], v[6:7], 0, v[28:29]
	v_lshl_add_u64 v[4:5], v[4:5], 2, s[0:1]
	v_lshl_add_u64 v[14:15], v[4:5], 0, v[28:29]
	global_load_dwordx4 v[4:7], v[12:13], off nt
	global_load_dwordx4 v[8:11], v[14:15], off nt
	v_add_u32_e32 v12, 16, v3
	v_mad_u64_u32 v[12:13], s[4:5], s6, v12, 0
	v_lshl_add_u64 v[12:13], v[12:13], 2, s[0:1]
	v_lshl_add_u64 v[20:21], v[12:13], 0, v[28:29]
	v_add_u32_e32 v12, 24, v3
	v_mad_u64_u32 v[12:13], s[4:5], s6, v12, 0
	v_lshl_add_u64 v[12:13], v[12:13], 2, s[0:1]
	v_lshl_add_u64 v[22:23], v[12:13], 0, v[28:29]
	global_load_dwordx4 v[12:15], v[20:21], off nt
	global_load_dwordx4 v[16:19], v[22:23], off nt
	v_add_u32_e32 v20, 32, v3
	v_mad_u64_u32 v[20:21], s[4:5], s6, v20, 0
	v_lshl_add_u64 v[20:21], v[20:21], 2, s[0:1]
	v_lshl_add_u64 v[30:31], v[20:21], 0, v[28:29]
	v_add_u32_e32 v20, 40, v3
	v_mad_u64_u32 v[20:21], s[4:5], s6, v20, 0
	v_lshl_add_u64 v[20:21], v[20:21], 2, s[0:1]
	v_lshl_add_u64 v[32:33], v[20:21], 0, v[28:29]
	global_load_dwordx4 v[20:23], v[30:31], off nt
	global_load_dwordx4 v[24:27], v[32:33], off nt
	v_add_u32_e32 v30, 48, v3
	v_mad_u64_u32 v[30:31], s[4:5], s6, v30, 0
	v_lshl_add_u64 v[30:31], v[30:31], 2, s[0:1]
	v_add_u32_e32 v3, 56, v3
	v_lshl_add_u64 v[36:37], v[30:31], 0, v[28:29]
	v_mad_u64_u32 v[30:31], s[4:5], s6, v3, 0
	v_lshl_add_u64 v[30:31], v[30:31], 2, s[0:1]
	v_lshl_add_u64 v[38:39], v[30:31], 0, v[28:29]
	global_load_dwordx4 v[32:35], v[36:37], off nt
	global_load_dwordx4 v[28:31], v[38:39], off nt

.LBB0_170:
	s_waitcnt vmcnt(6)
	v_add_u32_e32 v36, s10, v73
	v_add_u32_e32 v38, s10, v74
	s_waitcnt vmcnt(4)
	v_add_u32_e32 v44, s10, v75
	v_add_u32_e32 v46, s10, v76
	s_waitcnt vmcnt(2)
	v_add_u32_e32 v52, s10, v77
	v_add_u32_e32 v54, s10, v78
	s_waitcnt vmcnt(0)
	v_add_u32_e32 v62, s10, v79
	v_add_u32_e32 v64, s10, v80
	v_add_u32_e32 v70, s20, v70
	v_mad_u64_u32 v[36:37], s[18:19], s16, v36, 0
	v_mad_u64_u32 v[38:39], s[18:19], s16, v38, 0
	v_mad_u64_u32 v[44:45], s[18:19], s16, v44, 0
	v_mad_u64_u32 v[46:47], s[18:19], s16, v46, 0
	v_mad_u64_u32 v[52:53], s[18:19], s16, v52, 0
	v_mad_u64_u32 v[54:55], s[18:19], s16, v54, 0
	v_mad_u64_u32 v[62:63], s[18:19], s16, v62, 0
	v_mad_u64_u32 v[64:65], s[16:17], s16, v64, 0
	v_lshl_add_u64 v[36:37], v[36:37], 2, s[0:1]
	v_lshlrev_b64 v[60:61], 2, v[70:71]
	v_lshl_add_u64 v[38:39], v[38:39], 2, s[0:1]
	v_lshl_add_u64 v[44:45], v[44:45], 2, s[0:1]
	v_lshl_add_u64 v[46:47], v[46:47], 2, s[0:1]
	v_lshl_add_u64 v[52:53], v[52:53], 2, s[0:1]
	v_lshl_add_u64 v[54:55], v[54:55], 2, s[0:1]
	v_lshl_add_u64 v[62:63], v[62:63], 2, s[0:1]
	v_lshl_add_u64 v[64:65], v[64:65], 2, s[0:1]
	v_lshl_add_u64 v[36:37], v[36:37], 0, v[60:61]
	v_lshl_add_u64 v[38:39], v[38:39], 0, v[60:61]
	v_lshl_add_u64 v[44:45], v[44:45], 0, v[60:61]
	v_lshl_add_u64 v[46:47], v[46:47], 0, v[60:61]
	v_lshl_add_u64 v[52:53], v[52:53], 0, v[60:61]
	v_lshl_add_u64 v[54:55], v[54:55], 0, v[60:61]
	v_lshl_add_u64 v[62:63], v[62:63], 0, v[60:61]
	v_lshl_add_u64 v[60:61], v[64:65], 0, v[60:61]
	global_load_dwordx4 v[40:43], v[36:37], off nt
	s_nop 0
	global_load_dwordx4 v[36:39], v[38:39], off nt
	s_nop 0
	global_load_dwordx4 v[48:51], v[44:45], off nt
	s_nop 0
	global_load_dwordx4 v[44:47], v[46:47], off nt
	s_nop 0
	global_load_dwordx4 v[56:59], v[52:53], off nt
	s_nop 0
	global_load_dwordx4 v[52:55], v[54:55], off nt
	s_nop 0
	global_load_dwordx4 v[64:67], v[62:63], off nt
	s_nop 0
	global_load_dwordx4 v[60:63], v[60:61], off nt

.LBB0_201:
	s_waitcnt vmcnt(7)
	v_add_u32_e32 v4, s10, v73
	v_add_u32_e32 v6, s10, v74
	s_waitcnt vmcnt(5)
	v_add_u32_e32 v12, s10, v75
	v_add_u32_e32 v14, s10, v76
	s_waitcnt vmcnt(3)
	v_add_u32_e32 v20, s10, v77
	v_add_u32_e32 v22, s10, v78
	s_waitcnt vmcnt(0)
	v_add_u32_e32 v30, s10, v79
	v_add_u32_e32 v32, s10, v80
	v_add_u32_e32 v70, s22, v70
	v_mad_u64_u32 v[4:5], s[20:21], s18, v4, 0
	v_mad_u64_u32 v[6:7], s[20:21], s18, v6, 0
	v_mad_u64_u32 v[12:13], s[20:21], s18, v12, 0
	v_mad_u64_u32 v[14:15], s[20:21], s18, v14, 0
	v_mad_u64_u32 v[20:21], s[20:21], s18, v20, 0
	v_mad_u64_u32 v[22:23], s[20:21], s18, v22, 0
	v_mad_u64_u32 v[30:31], s[20:21], s18, v30, 0
	v_mad_u64_u32 v[32:33], s[18:19], s18, v32, 0
	v_lshl_add_u64 v[4:5], v[4:5], 2, s[0:1]
	v_lshlrev_b64 v[28:29], 2, v[70:71]
	v_lshl_add_u64 v[6:7], v[6:7], 2, s[0:1]
	v_lshl_add_u64 v[12:13], v[12:13], 2, s[0:1]
	v_lshl_add_u64 v[14:15], v[14:15], 2, s[0:1]
	v_lshl_add_u64 v[20:21], v[20:21], 2, s[0:1]
	v_lshl_add_u64 v[22:23], v[22:23], 2, s[0:1]
	v_lshl_add_u64 v[30:31], v[30:31], 2, s[0:1]
	v_lshl_add_u64 v[32:33], v[32:33], 2, s[0:1]
	v_lshl_add_u64 v[4:5], v[4:5], 0, v[28:29]
	v_lshl_add_u64 v[8:9], v[6:7], 0, v[28:29]
	v_lshl_add_u64 v[12:13], v[12:13], 0, v[28:29]
	v_lshl_add_u64 v[16:17], v[14:15], 0, v[28:29]
	v_lshl_add_u64 v[20:21], v[20:21], 0, v[28:29]
	v_lshl_add_u64 v[24:25], v[22:23], 0, v[28:29]
	v_lshl_add_u64 v[30:31], v[30:31], 0, v[28:29]
	v_lshl_add_u64 v[28:29], v[32:33], 0, v[28:29]
	global_load_dwordx4 v[4:7], v[4:5], off nt
	s_nop 0
	global_load_dwordx4 v[8:11], v[8:9], off nt
	s_nop 0
	global_load_dwordx4 v[12:15], v[12:13], off nt
	s_nop 0
	global_load_dwordx4 v[16:19], v[16:17], off nt
	s_nop 0
	global_load_dwordx4 v[20:23], v[20:21], off nt
	s_nop 0
	global_load_dwordx4 v[24:27], v[24:25], off nt
	s_nop 0
	global_load_dwordx4 v[32:35], v[30:31], off nt
	s_nop 0
	global_load_dwordx4 v[28:31], v[28:29], off nt
